# v045 g3(0): 96 converter CUs take 12288 gate/up items of layer 0; g1(0) takes 9984 w_down[0] items
# speedup vs baseline: 1.0128x; 1.0032x over previous
; DEV void phase_prologue_a(const Frame& F0) {
;     ...
;         constexpr int GU_NB = 2 * FF / 32, GU_ITEMS = 16 * GU_NB;
;         for (int it = F.gw; it < NE * GU_ITEMS; it += F.NGW) { const int e = it / GU_ITEMS, r = it % GU_ITEMS, kb = r / GU_NB, nb = r % GU_NB; const int d0 = 32 * nb, j = d0 >> 8, w = d0 & 255;
;             const float* src = (w < 128 ? GIN(I_WGATE) : GIN(I_WUP)) + ((size_t)l * NE + e) * 1024 * FF;
;             tr_item(src, FF, 128 * j + (w & 127), 64 * kb, (bf16_t*)(F.ws + WS_WGU) + ((size_t)l * NE + e) * 2 * FF * 1024, 1024, d0, scr, F.lane); }
.LBB0_24:
	s_andn2_b64 vcc, exec, s[10:11]
	s_cbranch_vccnz .LBB0_29
	s_lshl_b64 s[20:21], s[2:3], 27
	s_mov_b32 s28, s31
	v_readlane_b32 s100, v255, 51
	s_cmp_lg_u32 s100, 0x100
	s_cbranch_scc1 .Lpro_gu_all
	s_cmp_lg_u32 s14, 0
	s_cbranch_scc1 .LBB0_29
	s_add_i32 s28, s28, 0x3000

; DEV void phase_prologue_a(const Frame& F0) {
;     ...
;         constexpr int D_ITEMS = (FF / 64) * 32;
;         for (int it = F.gw; it < NE * D_ITEMS; it += F.NGW) { const int e = it / D_ITEMS, r = it % D_ITEMS, kb = r / 32, nb = r % 32;
;             tr_item(GIN(I_WDOWN) + ((size_t)l * NE + e) * FF * 1024, 1024, 32 * nb, 64 * kb, (bf16_t*)(F.ws + WS_WD) + ((size_t)l * NE + e) * 1024 * FF, FF, 32 * nb, scr, F.lane); }
.Lpro_dn_do:
	s_lshl_b64 s[20:21], s[2:3], 4
	s_mov_b32 s2, s31
	v_readlane_b32 s100, v255, 51
	s_cmp_lg_u32 s100, 0x100
	s_cbranch_scc1 .Lpro_dn_all
	s_cmp_lg_u32 s14, 0
	s_cbranch_scc1 .Lpro_dn_all
	s_add_i32 s2, s2, 0x2700

; #define LAS __attribute__((address_space(3)))
; #define NT_LOAD(p) __builtin_nontemporal_load(p)
; DEV void tr_item(const float* W, int ldw, int col0, int k0, bf16_t* WT, int K, int row0, LAS float* scr, int lane) {
; #pragma unroll 8
;     for (int i = 0; i < 32; ++i) { const int kk = 2 * i + (lane >> 5); scr[kk * 33 + (lane & 31)] = NT_LOAD(&W[(size_t)(k0 + kk) * ldw + col0 + (lane & 31)]); }
; DEV void phase_prologue_a(const Frame& F0) {
;     ...
;         constexpr int D_ITEMS = (FF / 64) * 32;
;         for (int it = F.gw; it < NE * D_ITEMS; it += F.NGW) { const int e = it / D_ITEMS, r = it % D_ITEMS, kb = r / 32, nb = r % 32;
;             tr_item(GIN(I_WDOWN) + ((size_t)l * NE + e) * FF * 1024, 1024, 32 * nb, 64 * kb, (bf16_t*)(F.ws + WS_WD) + ((size_t)l * NE + e) * 1024 * FF, FF, 32 * nb, scr, F.lane); }
.Lsh_dn_loop:
	s_lshr_b32 s8, s2, 10
	s_and_b32 s9, s2, 0x3ff
	s_lshr_b32 s10, s9, 5
	s_and_b32 s9, s9, 31
	s_lshl_b32 s24, s10, 18
	s_lshl_b32 s25, s9, 7
	s_add_i32 s24, s24, s25
	s_lshr_b32 s29, s8, 9
	s_lshl_b32 s28, s8, 23
	s_add_u32 s28, s28, s24
	s_addc_u32 s29, s29, 0
	s_add_u32 s28, s28, s4
	s_addc_u32 s29, s29, s5
	s_lshl_b32 s24, s9, 17
	s_lshl_b32 s25, s10, 7
	s_add_i32 s24, s24, s25
	s_lshr_b32 s11, s8, 10
	s_lshl_b32 s10, s8, 22
	s_add_u32 s10, s10, s24
	s_addc_u32 s11, s11, 0
	s_add_u32 s10, s10, s6
	s_addc_u32 s11, s11, s7
	v_lshl_add_u64 v[16:17], s[28:29], 0, v[122:123]
	v_lshl_add_u64 v[18:19], v[16:17], 0, s[44:45]
	v_lshl_add_u64 v[20:21], v[18:19], 0, s[44:45]
	v_lshl_add_u64 v[22:23], v[20:21], 0, s[44:45]
	v_lshl_add_u64 v[24:25], v[22:23], 0, s[44:45]
	v_lshl_add_u64 v[26:27], v[24:25], 0, s[44:45]
	v_lshl_add_u64 v[28:29], v[26:27], 0, s[44:45]
	v_lshl_add_u64 v[30:31], v[28:29], 0, s[44:45]
	global_load_dword v32, v[16:17], off nt
	global_load_dword v33, v[18:19], off nt
	global_load_dword v34, v[20:21], off nt
	global_load_dword v35, v[22:23], off nt
	global_load_dword v36, v[24:25], off nt
	global_load_dword v37, v[26:27], off nt
	global_load_dword v38, v[28:29], off nt
	global_load_dword v39, v[30:31], off nt
	v_lshl_add_u64 v[16:17], v[16:17], 0, s[40:41]
	v_lshl_add_u64 v[18:19], v[18:19], 0, s[40:41]
	v_lshl_add_u64 v[20:21], v[20:21], 0, s[40:41]
	v_lshl_add_u64 v[22:23], v[22:23], 0, s[40:41]
	v_lshl_add_u64 v[24:25], v[24:25], 0, s[40:41]
	v_lshl_add_u64 v[26:27], v[26:27], 0, s[40:41]
	v_lshl_add_u64 v[28:29], v[28:29], 0, s[40:41]
	v_lshl_add_u64 v[30:31], v[30:31], 0, s[40:41]
	global_load_dword v40, v[16:17], off nt
	global_load_dword v41, v[18:19], off nt
	global_load_dword v42, v[20:21], off nt
	global_load_dword v43, v[22:23], off nt
	global_load_dword v44, v[24:25], off nt
	global_load_dword v45, v[26:27], off nt
	global_load_dword v46, v[28:29], off nt
	global_load_dword v47, v[30:31], off nt
	v_lshl_add_u64 v[16:17], v[16:17], 0, s[40:41]
	v_lshl_add_u64 v[18:19], v[18:19], 0, s[40:41]
	v_lshl_add_u64 v[20:21], v[20:21], 0, s[40:41]
	v_lshl_add_u64 v[22:23], v[22:23], 0, s[40:41]
	v_lshl_add_u64 v[24:25], v[24:25], 0, s[40:41]
	v_lshl_add_u64 v[26:27], v[26:27], 0, s[40:41]
	v_lshl_add_u64 v[28:29], v[28:29], 0, s[40:41]
	v_lshl_add_u64 v[30:31], v[30:31], 0, s[40:41]
	global_load_dword v48, v[16:17], off nt
	global_load_dword v49, v[18:19], off nt
	global_load_dword v50, v[20:21], off nt
	global_load_dword v51, v[22:23], off nt
	global_load_dword v52, v[24:25], off nt
	global_load_dword v53, v[26:27], off nt
	global_load_dword v54, v[28:29], off nt
	global_load_dword v55, v[30:31], off nt
	v_lshl_add_u64 v[16:17], v[16:17], 0, s[40:41]
	v_lshl_add_u64 v[18:19], v[18:19], 0, s[40:41]
	v_lshl_add_u64 v[20:21], v[20:21], 0, s[40:41]
	v_lshl_add_u64 v[22:23], v[22:23], 0, s[40:41]
	v_lshl_add_u64 v[24:25], v[24:25], 0, s[40:41]
	v_lshl_add_u64 v[26:27], v[26:27], 0, s[40:41]
	v_lshl_add_u64 v[28:29], v[28:29], 0, s[40:41]
	v_lshl_add_u64 v[30:31], v[30:31], 0, s[40:41]
	global_load_dword v56, v[16:17], off nt
	global_load_dword v57, v[18:19], off nt
	global_load_dword v58, v[20:21], off nt
	global_load_dword v59, v[22:23], off nt
	global_load_dword v60, v[24:25], off nt
	global_load_dword v61, v[26:27], off nt
	global_load_dword v62, v[28:29], off nt
	global_load_dword v63, v[30:31], off nt
	v_lshl_add_u64 v[64:65], s[10:11], 0, v[124:125]
	v_lshl_add_u64 v[66:67], v[64:65], 0, s[42:43]
	v_lshl_add_u64 v[68:69], v[66:67], 0, s[42:43]
	v_lshl_add_u64 v[70:71], v[68:69], 0, s[42:43]
	s_add_i32 s31, s2, 0xc0
	s_lshr_b32 s8, s31, 10
	s_and_b32 s9, s31, 0x3ff
	s_lshr_b32 s10, s9, 5
	s_and_b32 s9, s9, 31
	s_lshl_b32 s24, s10, 18
	s_lshl_b32 s25, s9, 7
	s_add_i32 s24, s24, s25
	s_lshr_b32 s29, s8, 9
	s_lshl_b32 s28, s8, 23
	s_add_u32 s28, s28, s24
	s_addc_u32 s29, s29, 0
	s_add_u32 s28, s28, s4
	s_addc_u32 s29, s29, s5
	s_lshl_b32 s24, s9, 17
	s_lshl_b32 s25, s10, 7
	s_add_i32 s24, s24, s25
	s_lshr_b32 s11, s8, 10
	s_lshl_b32 s10, s8, 22
	s_add_u32 s10, s10, s24
	s_addc_u32 s11, s11, 0
	s_add_u32 s10, s10, s6
	s_addc_u32 s11, s11, s7
	v_lshl_add_u64 v[16:17], s[28:29], 0, v[122:123]
	v_lshl_add_u64 v[18:19], v[16:17], 0, s[44:45]
	v_lshl_add_u64 v[20:21], v[18:19], 0, s[44:45]
	v_lshl_add_u64 v[22:23], v[20:21], 0, s[44:45]
	v_lshl_add_u64 v[24:25], v[22:23], 0, s[44:45]
	v_lshl_add_u64 v[26:27], v[24:25], 0, s[44:45]
	v_lshl_add_u64 v[28:29], v[26:27], 0, s[44:45]
	v_lshl_add_u64 v[30:31], v[28:29], 0, s[44:45]
	global_load_dword v162, v[16:17], off nt
	global_load_dword v163, v[18:19], off nt
	global_load_dword v164, v[20:21], off nt
	global_load_dword v165, v[22:23], off nt
	global_load_dword v166, v[24:25], off nt
	global_load_dword v167, v[26:27], off nt
	global_load_dword v168, v[28:29], off nt
	global_load_dword v169, v[30:31], off nt
	v_lshl_add_u64 v[16:17], v[16:17], 0, s[40:41]
	v_lshl_add_u64 v[18:19], v[18:19], 0, s[40:41]
	v_lshl_add_u64 v[20:21], v[20:21], 0, s[40:41]
	v_lshl_add_u64 v[22:23], v[22:23], 0, s[40:41]
	v_lshl_add_u64 v[24:25], v[24:25], 0, s[40:41]
	v_lshl_add_u64 v[26:27], v[26:27], 0, s[40:41]
	v_lshl_add_u64 v[28:29], v[28:29], 0, s[40:41]
	v_lshl_add_u64 v[30:31], v[30:31], 0, s[40:41]
	global_load_dword v170, v[16:17], off nt
	global_load_dword v171, v[18:19], off nt
	global_load_dword v172, v[20:21], off nt
	global_load_dword v173, v[22:23], off nt
	global_load_dword v174, v[24:25], off nt
	global_load_dword v175, v[26:27], off nt
	global_load_dword v176, v[28:29], off nt
	global_load_dword v177, v[30:31], off nt
	v_lshl_add_u64 v[16:17], v[16:17], 0, s[40:41]
; #define WAVE_LDS_SYNC() do { int _z = 0; (void)emu::wave_xchg(&_z, 4); } while (0)
; #define LAS __attribute__((address_space(3)))
; #define WAVE_LDS_SYNC() asm volatile("s_waitcnt lgkmcnt(0)" ::: "memory")
; #define NT_LOAD(p) __builtin_nontemporal_load(p)
; DEV void tr_item(const float* W, int ldw, int col0, int k0, bf16_t* WT, int K, int row0, LAS float* scr, int lane) {
; #pragma unroll 8
;     for (int i = 0; i < 32; ++i) { const int kk = 2 * i + (lane >> 5); scr[kk * 33 + (lane & 31)] = NT_LOAD(&W[(size_t)(k0 + kk) * ldw + col0 + (lane & 31)]); }
;     WAVE_LDS_SYNC();
;     const int c = lane & 7;
; #pragma unroll
	v_lshl_add_u64 v[18:19], v[18:19], 0, s[40:41]
	v_lshl_add_u64 v[20:21], v[20:21], 0, s[40:41]
	v_lshl_add_u64 v[22:23], v[22:23], 0, s[40:41]
	v_lshl_add_u64 v[24:25], v[24:25], 0, s[40:41]
	v_lshl_add_u64 v[26:27], v[26:27], 0, s[40:41]
	v_lshl_add_u64 v[28:29], v[28:29], 0, s[40:41]
	v_lshl_add_u64 v[30:31], v[30:31], 0, s[40:41]
	global_load_dword v178, v[16:17], off nt
	global_load_dword v179, v[18:19], off nt
	global_load_dword v180, v[20:21], off nt
	global_load_dword v181, v[22:23], off nt
	global_load_dword v182, v[24:25], off nt
	global_load_dword v183, v[26:27], off nt
	global_load_dword v184, v[28:29], off nt
	global_load_dword v185, v[30:31], off nt
	v_lshl_add_u64 v[16:17], v[16:17], 0, s[40:41]
	v_lshl_add_u64 v[18:19], v[18:19], 0, s[40:41]
	v_lshl_add_u64 v[20:21], v[20:21], 0, s[40:41]
	v_lshl_add_u64 v[22:23], v[22:23], 0, s[40:41]
	v_lshl_add_u64 v[24:25], v[24:25], 0, s[40:41]
	v_lshl_add_u64 v[26:27], v[26:27], 0, s[40:41]
	v_lshl_add_u64 v[28:29], v[28:29], 0, s[40:41]
	v_lshl_add_u64 v[30:31], v[30:31], 0, s[40:41]
	global_load_dword v186, v[16:17], off nt
	global_load_dword v187, v[18:19], off nt
	global_load_dword v188, v[20:21], off nt
	global_load_dword v189, v[22:23], off nt
	global_load_dword v190, v[24:25], off nt
	global_load_dword v191, v[26:27], off nt
	global_load_dword v192, v[28:29], off nt
	global_load_dword v193, v[30:31], off nt
	v_lshl_add_u64 v[126:127], s[10:11], 0, v[124:125]
	v_lshl_add_u64 v[128:129], v[126:127], 0, s[42:43]
	v_lshl_add_u64 v[130:131], v[128:129], 0, s[42:43]
	v_lshl_add_u64 v[132:133], v[130:131], 0, s[42:43]
	s_waitcnt vmcnt(62)
	ds_write2_b32 v7, v32, v33 offset1:66
	s_waitcnt vmcnt(60)
	ds_write2_b32 v7, v34, v35 offset0:132 offset1:198
	s_waitcnt vmcnt(58)
	ds_write2_b32 v8, v36, v37 offset0:8 offset1:74
	s_waitcnt vmcnt(56)
	ds_write2_b32 v8, v38, v39 offset0:140 offset1:206
	s_waitcnt vmcnt(54)
	ds_write2_b32 v9, v40, v41 offset1:66
	s_waitcnt vmcnt(52)
	ds_write2_b32 v9, v42, v43 offset0:132 offset1:198
	s_waitcnt vmcnt(50)
	ds_write2_b32 v10, v44, v45 offset0:8 offset1:74
	s_waitcnt vmcnt(48)
	ds_write2_b32 v10, v46, v47 offset0:140 offset1:206
	s_waitcnt vmcnt(46)
	ds_write2_b32 v11, v48, v49 offset1:66
	s_waitcnt vmcnt(44)
	ds_write2_b32 v11, v50, v51 offset0:132 offset1:198
	s_waitcnt vmcnt(42)
	ds_write2_b32 v12, v52, v53 offset0:8 offset1:74
	s_waitcnt vmcnt(40)
	ds_write2_b32 v12, v54, v55 offset0:140 offset1:206
	s_waitcnt vmcnt(38)
	ds_write2_b32 v13, v56, v57 offset1:66
	s_waitcnt vmcnt(36)
	ds_write2_b32 v13, v58, v59 offset0:132 offset1:198
	s_waitcnt vmcnt(34)
	ds_write2_b32 v14, v60, v61 offset0:8 offset1:74
	s_waitcnt vmcnt(32)
	ds_write2_b32 v14, v62, v63 offset0:140 offset1:206
	ds_read2_b32 v[72:73], v15 offset1:8
	ds_read2_b32 v[74:75], v15 offset0:33 offset1:41
	ds_read2_b32 v[76:77], v15 offset0:66 offset1:74
	ds_read2_b32 v[78:79], v15 offset0:99 offset1:107
	ds_read2_b32 v[80:81], v15 offset0:132 offset1:140
	ds_read2_b32 v[82:83], v15 offset0:165 offset1:173
	ds_read2_b32 v[84:85], v15 offset0:198 offset1:206
	ds_read2_b32 v[86:87], v15 offset0:231 offset1:239
	ds_read2_b32 v[88:89], v15 offset0:16 offset1:24
	ds_read2_b32 v[90:91], v15 offset0:49 offset1:57
	ds_read2_b32 v[92:93], v15 offset0:82 offset1:90
	ds_read2_b32 v[94:95], v15 offset0:115 offset1:123
	s_waitcnt lgkmcnt(4)
; #define LAS __attribute__((address_space(3)))
; #define NT_STORE(v, p) __builtin_nontemporal_store((v), (p))
; DEV unsigned pk2(float lo, float hi) { return f2bf(lo) | (f2bf(hi) << 16); }
; DEV unsigned pk2(float lo, float hi) { const f32x2n_t v = {lo, hi}; return __builtin_bit_cast(unsigned, __builtin_convertvector(v, bf16x2n_t)); }
; DEV void tr_item(const float* W, int ldw, int col0, int k0, bf16_t* WT, int K, int row0, LAS float* scr, int lane) {
;     ...
;     const int c = lane & 7;
; #pragma unroll
;     for (int j = 0; j < 4; ++j) { const int n = (lane >> 3) + 8 * j; const LAS float* s = scr + (8 * c) * 33 + n;
;         u32x4 o; o.x = pk2(s[0 * 33], s[1 * 33]); o.y = pk2(s[2 * 33], s[3 * 33]); o.z = pk2(s[4 * 33], s[5 * 33]); o.w = pk2(s[6 * 33], s[7 * 33]);
;         NT_STORE(o, (u32x4*)(WT + (size_t)(row0 + n) * K + k0 + 8 * c)); }
; DEV void phase_prologue_a(const Frame& F0) {
;     ...
;         constexpr int D_ITEMS = (FF / 64) * 32;
;         for (int it = F.gw; it < NE * D_ITEMS; it += F.NGW) { const int e = it / D_ITEMS, r = it % D_ITEMS, kb = r / 32, nb = r % 32;
;             tr_item(GIN(I_WDOWN) + ((size_t)l * NE + e) * FF * 1024, 1024, 32 * nb, 64 * kb, (bf16_t*)(F.ws + WS_WD) + ((size_t)l * NE + e) * 1024 * FF, FF, 32 * nb, scr, F.lane); }
	v_cvt_pk_bf16_f32 v104, v72, v74
	v_cvt_pk_bf16_f32 v105, v76, v78
	v_cvt_pk_bf16_f32 v106, v80, v82
	v_cvt_pk_bf16_f32 v107, v84, v86
	v_cvt_pk_bf16_f32 v108, v73, v75
	v_cvt_pk_bf16_f32 v109, v77, v79
	v_cvt_pk_bf16_f32 v110, v81, v83
	v_cvt_pk_bf16_f32 v111, v85, v87
	ds_read2_b32 v[96:97], v15 offset0:148 offset1:156
	ds_read2_b32 v[98:99], v15 offset0:181 offset1:189
	ds_read2_b32 v[100:101], v15 offset0:214 offset1:222
	ds_read2_b32 v[102:103], v15 offset0:247 offset1:255
	global_store_dwordx4 v[64:65], v[104:107], off nt
	global_store_dwordx4 v[66:67], v[108:111], off nt
	s_waitcnt lgkmcnt(0)
	v_cvt_pk_bf16_f32 v112, v88, v90
	v_cvt_pk_bf16_f32 v113, v92, v94
	v_cvt_pk_bf16_f32 v114, v96, v98
	v_cvt_pk_bf16_f32 v115, v100, v102
	v_cvt_pk_bf16_f32 v116, v89, v91
	v_cvt_pk_bf16_f32 v117, v93, v95
	v_cvt_pk_bf16_f32 v118, v97, v99
	v_cvt_pk_bf16_f32 v119, v101, v103
	global_store_dwordx4 v[68:69], v[112:115], off nt
	global_store_dwordx4 v[70:71], v[116:119], off nt
	s_waitcnt vmcnt(34)
	ds_write2_b32 v7, v162, v163 offset1:66
	s_waitcnt vmcnt(32)
	ds_write2_b32 v7, v164, v165 offset0:132 offset1:198
	s_waitcnt vmcnt(30)
	ds_write2_b32 v8, v166, v167 offset0:8 offset1:74
	s_waitcnt vmcnt(28)
	ds_write2_b32 v8, v168, v169 offset0:140 offset1:206
	s_waitcnt vmcnt(26)
	ds_write2_b32 v9, v170, v171 offset1:66
	s_waitcnt vmcnt(24)
	ds_write2_b32 v9, v172, v173 offset0:132 offset1:198
	s_waitcnt vmcnt(22)
	ds_write2_b32 v10, v174, v175 offset0:8 offset1:74
	s_waitcnt vmcnt(20)
	ds_write2_b32 v10, v176, v177 offset0:140 offset1:206
	s_waitcnt vmcnt(18)
	ds_write2_b32 v11, v178, v179 offset1:66
	s_waitcnt vmcnt(16)
	ds_write2_b32 v11, v180, v181 offset0:132 offset1:198
	s_waitcnt vmcnt(14)
	ds_write2_b32 v12, v182, v183 offset0:8 offset1:74
	s_waitcnt vmcnt(12)
	ds_write2_b32 v12, v184, v185 offset0:140 offset1:206
	s_waitcnt vmcnt(10)
	ds_write2_b32 v13, v186, v187 offset1:66
	s_waitcnt vmcnt(8)
	ds_write2_b32 v13, v188, v189 offset0:132 offset1:198
	s_waitcnt vmcnt(6)
	ds_write2_b32 v14, v190, v191 offset0:8 offset1:74
	s_waitcnt vmcnt(4)
	ds_write2_b32 v14, v192, v193 offset0:140 offset1:206
	ds_read2_b32 v[72:73], v15 offset1:8
	ds_read2_b32 v[74:75], v15 offset0:33 offset1:41
	ds_read2_b32 v[76:77], v15 offset0:66 offset1:74
	ds_read2_b32 v[78:79], v15 offset0:99 offset1:107
	ds_read2_b32 v[80:81], v15 offset0:132 offset1:140
	ds_read2_b32 v[82:83], v15 offset0:165 offset1:173
	ds_read2_b32 v[84:85], v15 offset0:198 offset1:206
	ds_read2_b32 v[86:87], v15 offset0:231 offset1:239
	ds_read2_b32 v[88:89], v15 offset0:16 offset1:24
	ds_read2_b32 v[90:91], v15 offset0:49 offset1:57
	ds_read2_b32 v[92:93], v15 offset0:82 offset1:90
	ds_read2_b32 v[94:95], v15 offset0:115 offset1:123
	s_waitcnt lgkmcnt(4)
	v_cvt_pk_bf16_f32 v104, v72, v74
	v_cvt_pk_bf16_f32 v105, v76, v78
	v_cvt_pk_bf16_f32 v106, v80, v82
	v_cvt_pk_bf16_f32 v107, v84, v86
	v_cvt_pk_bf16_f32 v108, v73, v75
	v_cvt_pk_bf16_f32 v109, v77, v79
	v_cvt_pk_bf16_f32 v110, v81, v83
	v_cvt_pk_bf16_f32 v111, v85, v87
	ds_read2_b32 v[96:97], v15 offset0:148 offset1:156
	ds_read2_b32 v[98:99], v15 offset0:181 offset1:189
	ds_read2_b32 v[100:101], v15 offset0:214 offset1:222
	ds_read2_b32 v[102:103], v15 offset0:247 offset1:255
	global_store_dwordx4 v[126:127], v[104:107], off nt
	global_store_dwordx4 v[128:129], v[108:111], off nt
	s_waitcnt lgkmcnt(0)
	v_cvt_pk_bf16_f32 v112, v88, v90
	v_cvt_pk_bf16_f32 v113, v92, v94
	v_cvt_pk_bf16_f32 v114, v96, v98
	v_cvt_pk_bf16_f32 v115, v100, v102
	v_cvt_pk_bf16_f32 v116, v89, v91
	v_cvt_pk_bf16_f32 v117, v93, v95
	v_cvt_pk_bf16_f32 v118, v97, v99
	v_cvt_pk_bf16_f32 v119, v101, v103
	global_store_dwordx4 v[130:131], v[112:115], off nt
	global_store_dwordx4 v[132:133], v[116:119], off nt
	s_add_i32 s2, s2, 0x180
	s_cmp_lt_u32 s2, 0x2700
	s_cbranch_scc1 .Lsh_dn_loop
	s_branch .Lsh_done

; template <class Epi, class Sched>
; DEV void gemm_phase(LAS unsigned char* lds, const int K, const Sched& S, const Epi& E, const int wid, const int lane) {
;     const int tid = wid * 64 + lane; const int wr = wid >> 2, wc = wid & 3, fr = lane & 15, fq = lane >> 4;
;     const int nt = K / BK;
;     unsigned voffA[2], voffB[2]; int Ri[2], Ci[2];
; #pragma unroll
;     for (int i = 0; i < 2; ++i) { int R, C; stage_rc(tid * 16 + i * 8192, R, C); const int Rb = Epi::PERM ? ((R & ~31) + perm32(R & 31)) : R; Ri[i] = R; Ci[i] = C;
;         voffA[i] = (unsigned)(R * K + C) * 2u; voffB[i] = (unsigned)(Rb * K + C) * 2u; }
;     unsigned goffC[2][2] = {{0u, 0u}, {0u, 0u}}, goffN[2][2] = {{0u, 0u}, {0u, 0u}};
;     constexpr int GIDX_OFF = STAGE_BYTES;
;     const size_t kstep = (size_t)(BK * 2);
;     const size_t hstep = (size_t)HALF * K * 2;
;     const unsigned ldsw = (unsigned)wid * 1024u;
;     const int aoff = lds_byte(wr * 64 + fr, fq * 8), boff = lds_byte(wc * 32 + fr, fq * 8);
;     ...
;     Unit cur, nxt; int ui = 0;
;     if (!S.next(0, cur)) return;
;     f32x4 acc[2][2][4][2];
; #pragma unroll
;     for (int a = 0; a < 2; ++a)
; #pragma unroll
;         for (int b = 0; b < 2; ++b)
; #pragma unroll
;             for (int m = 0; m < 4; ++m)
; #pragma unroll
;                 for (int n = 0; n < 2; ++n) acc[a][b][m][n] = (f32x4){0.f, 0.f, 0.f, 0.f};
;     bf16x8 At[4][2], B0[2][2], B1[2][2];
;     const char* cA = cur.A; const char* cB = cur.B;
;     if constexpr (Sched::GATHER_A) {
; #pragma unroll
;         for (int hh = 0; hh < 2; ++hh)
; #pragma unroll
;             for (int i = 0; i < 2; ++i) { goffC[hh][i] = (unsigned)S.gidx[S.idx_base(cur) + hh * HALF + Ri[i]] * (unsigned)(K * 2) + (unsigned)(Ci[i] * 2); goffN[hh][i] = goffC[hh][i]; }
;     }
;     PG8_STAGE(PG8_SB(0, 0), cB, voffB); PG8_STAGE(PG8_SB(0, 1), cB + hstep, voffB); PG8_STAGEA(PG8_SA(0, 0), cA, 0, false); PG8_STAGEA(PG8_SA(0, 1), cA, 1, false);
;     if (wr == 1) S_BARRIER();
;     WAIT_VM(2); S_BARRIER();
; DEV void gemm_g3(const Frame& F0, int l, int vcu) {
;     const Frame F = refresh(F0);
;     pg8::PlainOrder S; S.init((const void*)(F.ws + WS_MERGED), (const bf16_t*)(F.ws + WS_WOUT) + (size_t)l * 1024 * 1024, 1024, (l == DEPTH - 1) ? LATPAD : MPAD, 1024, F.G, vcu);
;     EpiP E; E.O = (bf16_t*)(F.ws + WS_Y); E.ldc = 1024;
;     pg8::gemm_phase(F.lds, 1024, S, E, F.wave, F.lane);
; }
.LBB0_1317:
	v_readlane_b32 s4, v251, 0
	v_readlane_b32 s6, v251, 2
	v_readlane_b32 s7, v251, 3
	s_lshl_b32 s0, s33, 2
	v_readlane_b32 s10, v251, 29
	v_mov_b32_e32 v16, v200
	s_mov_b64 s[2:3], s[6:7]
	s_cmp_ge_i32 s95, s0
	v_readlane_b32 s5, v251, 1
	s_cbranch_scc1 .LBB0_1333
	s_mov_b32 s100, s96
	v_readlane_b32 s101, v253, 62
	s_cmp_lg_u32 s101, 0
	s_cbranch_scc1 .Lg3d_norm
	v_readlane_b32 s101, v255, 51
	s_cmp_lg_u32 s101, 0x100
	s_cbranch_scc1 .Lg3d_norm
	s_movk_i32 s100, 0xa0
	v_readlane_b32 s101, v255, 48
	s_cmp_ge_u32 s101, 0xa0
	s_cbranch_scc1 .Lsg_entry
.Lg3d_norm:
	v_readlane_b32 s4, v253, 62
	s_add_u32 s26, s2, 0x393a8800
	v_readlane_b32 s5, v253, 63
	s_addc_u32 s27, s3, 0
	s_lshl_b64 s[4:5], s[4:5], 21
	s_add_u32 s4, s2, s4
	s_addc_u32 s5, s3, s5
	s_add_u32 s28, s4, 0x22c8000
	s_addc_u32 s29, s5, 0
	s_lshl_b32 s30, s10, 10
	v_lshl_add_u32 v0, v16, 4, s30
	v_add_u32_e32 v2, 0x2000, v0
	v_ashrrev_i32_e32 v3, 31, v2
	v_lshrrev_b32_e32 v3, 22, v3
	v_add_u32_e32 v3, v2, v3
	v_ashrrev_i32_e32 v10, 10, v3
	v_mul_i32_i24_e32 v3, 0x400, v10
	v_sub_u32_e32 v2, v2, v3
	v_lshrrev_b32_e32 v3, 4, v2
	v_bitop3_b32 v2, v3, v2, 32 bitop3:0x6c
	v_ashrrev_i32_e32 v3, 31, v2
	v_lshrrev_b32_e32 v3, 26, v3
	v_add_u32_e32 v3, v2, v3
	v_ashrrev_i32_e32 v11, 6, v3
	v_lshlrev_b32_e32 v4, 3, v10
	v_and_b32_e32 v3, 0xffc0, v3
	v_and_b32_e32 v4, -16, v4
	v_sub_u32_e32 v2, v2, v3
	v_add_u32_e32 v4, v11, v4
	v_lshrrev_b16_e32 v3, 7, v2
	v_and_b32_e32 v5, 3, v11
	s_mov_b32 s4, 0x1fffe0
	v_lshrrev_b32_e32 v6, 2, v4
	v_lshlrev_b32_e32 v7, 1, v4
	v_and_b32_e32 v3, 1, v3
	v_and_or_b32 v5, v4, s4, v5
	v_and_b32_e32 v6, 4, v6
	v_and_b32_e32 v7, 24, v7
	v_add_u16_e32 v2, v2, v3
	v_or3_b32 v5, v5, v6, v7
	v_lshlrev_b32_e32 v6, 5, v10
	v_ashrrev_i16_sdwa v2, v202, sext(v2) dst_sel:DWORD dst_unused:UNUSED_PAD src0_sel:DWORD src1_sel:BYTE_0
	v_and_b32_e32 v6, 32, v6
	v_bfe_i32 v13, v2, 0, 16
	v_add_lshl_u32 v2, v6, v13, 1
	v_lshl_add_u32 v130, v5, 11, v2
	v_lshl_add_u32 v132, v4, 11, v2
	v_ashrrev_i32_e32 v2, 31, v0
	v_lshrrev_b32_e32 v2, 22, v2
	v_add_u32_e32 v2, v0, v2
	v_ashrrev_i32_e32 v12, 10, v2
	v_mul_i32_i24_e32 v2, 0x400, v12
	v_sub_u32_e32 v0, v0, v2
	v_lshrrev_b32_e32 v2, 4, v0
	v_bitop3_b32 v0, v2, v0, 32 bitop3:0x6c
	v_ashrrev_i32_e32 v2, 31, v0
	v_lshrrev_b32_e32 v2, 26, v2
	v_add_u32_e32 v2, v0, v2
	v_lshlrev_b32_e32 v3, 3, v12
	v_ashrrev_i32_e32 v14, 6, v2
	v_and_b32_e32 v3, -16, v3
	v_add_u32_e32 v3, v14, v3
	v_and_b32_e32 v4, 3, v14
	v_and_or_b32 v4, v3, s4, v4
	s_lshr_b32 s31, s33, 1
	v_readlane_b32 s4, v252, 24
	s_ashr_i32 s11, s10, 2
	s_or_b32 s34, s31, 1
	v_readlane_b32 s5, v252, 25
	s_and_b64 s[4:5], s[4:5], exec
	s_cselect_b32 s4, s34, s31
	v_readlane_b32 s5, v252, 23
	s_mul_i32 s4, s4, s5
	v_readlane_b32 s5, v252, 21
	s_add_i32 s4, s4, s5
	s_ashr_i32 s5, s4, 31
	s_lshr_b32 s5, s5, 27
	s_add_i32 s5, s4, s5
	v_lshrrev_b32_e32 v5, 2, v3
	v_lshlrev_b32_e32 v6, 1, v3
	v_and_b32_e32 v2, 0xc0, v2
	s_ashr_i32 s6, s5, 5
	v_and_b32_e32 v5, 4, v5
	v_and_b32_e32 v6, 24, v6
	v_sub_u32_e32 v0, v0, v2
	s_lshl_b32 s7, s6, 3
	v_or3_b32 v4, v4, v5, v6
	v_lshlrev_b32_e32 v5, 5, v12
	v_ashrrev_i16_sdwa v0, v202, sext(v0) dst_sel:DWORD dst_unused:UNUSED_PAD src0_sel:DWORD src1_sel:BYTE_0
	s_sub_i32 s6, s33, s7
	v_and_b32_e32 v5, 32, v5
	v_bfe_i32 v15, v0, 0, 16
	s_min_u32 s8, s6, 8
	s_andn2_b32 s5, s5, 31
	v_add_lshl_u32 v2, v5, v15, 1
	s_sub_i32 s9, s4, s5
	v_cvt_f32_ubyte0_e32 v5, s8
	v_lshl_add_u32 v0, v4, 11, v2
	v_cvt_f32_i32_e32 v4, s9
	v_rcp_iflag_f32_e32 v6, v5
	v_lshl_add_u32 v134, v3, 11, v2
	s_ashr_i32 s4, s9, 30
	s_or_b32 s6, s4, 1
	v_mul_f32_e32 v2, v4, v6
	v_trunc_f32_e32 v2, v2
	v_fma_f32 v3, -v2, v5, v4
	v_cvt_i32_f32_e32 v2, v2
	v_cmp_ge_f32_e64 s[4:5], |v3|, v5
	s_and_b64 s[4:5], s[4:5], exec
	s_cselect_b32 s4, s6, 0
	v_readfirstlane_b32 s5, v2
	s_add_i32 s6, s5, s4
	s_mul_i32 s4, s6, s8
	s_sub_i32 s4, s9, s4
	s_sext_i32_i8 s4, s4
	s_add_i32 s8, s7, s4
	s_ashr_i32 s9, s8, 31
	s_lshl_b64 s[4:5], s[8:9], 19
	s_add_u32 s20, s26, s4
	s_addc_u32 s21, s27, s5
	s_bfe_i64 s[4:5], s[6:7], 0x80000
	s_lshl_b64 s[4:5], s[4:5], 19
	s_add_u32 s22, s28, s4
	s_addc_u32 s23, s29, s5
	s_add_i32 s9, s30, 0
	s_add_i32 m0, s9, 0x10000
	v_add_u32_e32 v136, 0x40000, v134
	global_load_lds_dwordx4 v0, s[22:23]
	s_add_i32 m0, s9, 0x12000
	s_add_u32 s4, s22, 0x40000
	global_load_lds_dwordx4 v130, s[22:23]
	s_addc_u32 s5, s23, 0
	s_add_i32 m0, s9, 0x14000
	s_add_i32 s35, s9, 0x2000
	global_load_lds_dwordx4 v0, s[4:5]
	s_add_i32 m0, s9, 0x16000
	s_add_i32 s36, s9, 0x4000
	global_load_lds_dwordx4 v130, s[4:5]
	s_mov_b32 m0, s9
	s_add_i32 s37, s9, 0x6000
	global_load_lds_dwordx4 v134, s[20:21]
	s_mov_b32 m0, s35
	v_add_u32_e32 v138, 0x40000, v132
	global_load_lds_dwordx4 v132, s[20:21]
	s_mov_b32 m0, s36
	v_mov_b32_e32 v131, v1
	global_load_lds_dwordx4 v136, s[20:21]
	s_mov_b32 m0, s37
	v_mov_b32_e32 v135, v1
	global_load_lds_dwordx4 v138, s[20:21]
	v_mov_b32_e32 v133, v1
	s_cmp_eq_u32 s11, 1
	v_lshl_add_u64 v[8:9], s[22:23], 0, v[0:1]
	v_lshl_add_u64 v[6:7], s[22:23], 0, v[130:131]
	v_lshl_add_u64 v[2:3], s[20:21], 0, v[134:135]
	s_cselect_b64 s[4:5], -1, 0
	s_cmp_lg_u32 s11, 1
	v_lshl_add_u64 v[4:5], s[20:21], 0, v[132:133]
	s_cbranch_scc1 .LBB0_1320
	s_barrier

;     DEV bool next(int i, Unit& u) const { if (!GroupedOrder::next(i, u)) return false; u.A = A; return true; }
;     DEV bool next(int i, Unit& u) const {
;         const long L = (long)i * G + c; if (L >= nwg) return false;
;         int wgid = (int)L; { const int q = nwg / 8, r = nwg % 8, xcd = wgid % 8, off = wgid / 8; wgid = (xcd < r ? xcd * (q + 1) : r * (q + 1) + (xcd - r) * q) + off; }
;         const int nig = 8 * nN, gid = wgid / nig, fm = gid * 8, gsz = (nM - fm) < 8 ? (nM - fm) : 8;
;         u.pm = fm + ((wgid % nig) % gsz); u.pn = (wgid % nig) / gsz; u.e = 0;
;         u.A = A + (size_t)u.pm * BM * K * 2; u.B = Bt + (size_t)u.pn * BM * K * 2; return true;
.LBB0_1323:
	s_add_i32 s40, s40, 1
	s_mul_i32 s2, s40, s83
	s_mul_hi_u32 s3, s40, s100
	s_add_i32 s3, s3, s2
	s_mul_i32 s2, s40, s100
	s_add_u32 s24, s2, s95
	s_addc_u32 s25, s3, s81
	v_mov_b64_e32 v[2:3], s[0:1]
	v_cmp_ge_i64_e32 vcc, s[24:25], v[2:3]
	v_cmp_lt_i64_e64 s[2:3], s[24:25], v[2:3]
	s_cbranch_vccnz .LBB0_1325
	s_ashr_i32 s12, s24, 31
	s_lshr_b32 s12, s12, 29
	s_add_i32 s12, s24, s12
	s_ashr_i32 s13, s12, 3
	s_and_b32 s12, s12, -8
	s_sub_i32 s12, s24, s12
	s_cmp_lt_i32 s12, 0
	s_cselect_b32 s14, s34, s31
	s_mul_i32 s12, s14, s12
	s_add_i32 s12, s12, s13
	s_ashr_i32 s13, s12, 31
	s_lshr_b32 s13, s13, 27
	s_add_i32 s13, s12, s13
	s_ashr_i32 s14, s13, 5
	s_lshl_b32 s14, s14, 3
	s_sub_i32 s15, s33, s14
	s_min_i32 s15, s15, 8
	s_abs_i32 s16, s15
	v_cvt_f32_u32_e32 v2, s16
	s_sub_i32 s18, 0, s16
	s_andn2_b32 s13, s13, 31
	s_sub_i32 s13, s12, s13
	v_rcp_iflag_f32_e32 v2, v2
	s_abs_i32 s12, s13
	s_xor_b32 s17, s13, s15
	s_ashr_i32 s17, s17, 31
	v_mul_f32_e32 v2, 0x4f7ffffe, v2
	v_cvt_u32_f32_e32 v2, v2
	s_nop 0
	v_readfirstlane_b32 s19, v2
	s_mul_i32 s18, s18, s19
	s_mul_hi_u32 s18, s19, s18
	s_add_i32 s19, s19, s18
	s_mul_hi_u32 s18, s12, s19
	s_mul_i32 s19, s18, s16
	s_sub_i32 s12, s12, s19
	s_add_i32 s24, s18, 1
	s_sub_i32 s19, s12, s16
	s_cmp_ge_u32 s12, s16
	s_cselect_b32 s18, s24, s18
	s_cselect_b32 s12, s19, s12
	s_add_i32 s19, s18, 1
	s_cmp_ge_u32 s12, s16
	s_cselect_b32 s12, s19, s18
	s_xor_b32 s12, s12, s17
	s_sub_i32 s12, s12, s17
	s_mul_i32 s15, s12, s15
	s_sub_i32 s13, s13, s15
	s_add_i32 s14, s13, s14
	s_ashr_i32 s15, s14, 31
	s_lshl_b64 s[16:17], s[14:15], 19
	s_add_u32 s16, s26, s16
	s_addc_u32 s17, s27, s17
	s_ashr_i32 s13, s12, 31
	s_lshl_b64 s[18:19], s[12:13], 19
	s_add_u32 s18, s28, s18
	s_addc_u32 s19, s29, s19

; #define LAS __attribute__((address_space(3)))
; #define NT_LOAD(p) __builtin_nontemporal_load(p)
; DEV void tr_item(const float* W, int ldw, int col0, int k0, bf16_t* WT, int K, int row0, LAS float* scr, int lane) {
; #pragma unroll 8
;     for (int i = 0; i < 32; ++i) { const int kk = 2 * i + (lane >> 5); scr[kk * 33 + (lane & 31)] = NT_LOAD(&W[(size_t)(k0 + kk) * ldw + col0 + (lane & 31)]); }
; DEV void phase_prologue_a(const Frame& F0) {
;     ...
;         constexpr int GU_NB = 2 * FF / 32, GU_ITEMS = 16 * GU_NB;
;         for (int it = F.gw; it < NE * GU_ITEMS; it += F.NGW) { const int e = it / GU_ITEMS, r = it % GU_ITEMS, kb = r / GU_NB, nb = r % GU_NB; const int d0 = 32 * nb, j = d0 >> 8, w = d0 & 255;
;             const float* src = (w < 128 ? GIN(I_WGATE) : GIN(I_WUP)) + ((size_t)l * NE + e) * 1024 * FF;
;             tr_item(src, FF, 128 * j + (w & 127), 64 * kb, (bf16_t*)(F.ws + WS_WGU) + ((size_t)l * NE + e) * 2 * FF * 1024, 1024, d0, scr, F.lane); }
.Lsg_entry:
	v_readlane_b32 s2, v253, 62
	s_cmp_lg_u32 s2, 0
	s_cbranch_scc1 .Lsg_done
	v_readlane_b32 s2, v255, 51
	s_cmp_lg_u32 s2, 0x100
	s_cbranch_scc1 .Lsg_done
	v_readlane_b32 s2, v255, 48
	s_cmp_lt_u32 s2, 0xa0
	s_cbranch_scc1 .Lsg_done
	v_readlane_b32 s3, v251, 29
	s_sub_i32 s2, s2, 0xa0
	s_lshl_b32 s2, s2, 3
	s_add_i32 s2, s2, s3
	v_readlane_b32 s6, v255, 53
	v_readlane_b32 s7, v255, 54
	v_readlane_b32 s4, v255, 55
	v_readlane_b32 s5, v255, 56
	v_readlane_b32 s34, v255, 57
	v_readlane_b32 s35, v255, 58
	s_add_u32 s6, s6, 0x2bc8000
	s_addc_u32 s7, s7, 0
	s_lshl_b32 s30, s3, 14
	v_and_b32_e32 v120, 31, v200
	v_lshlrev_b32_e32 v2, 2, v120
	v_lshrrev_b32_e32 v3, 5, v200
	v_and_b32_e32 v4, 7, v200
	v_lshrrev_b32_e32 v6, 3, v200
	v_mul_u32_u24_e32 v7, 33, v3
	v_add_u32_e32 v7, v7, v120
	v_lshl_add_u32 v7, v7, 2, s30
	v_add_u32_e32 v8, 0x400, v7
	v_add_u32_e32 v9, 0x840, v7
	v_add_u32_e32 v10, 0xc40, v7
	v_add_u32_e32 v11, 0x1080, v7
	v_add_u32_e32 v12, 0x1480, v7
	v_add_u32_e32 v13, 0x18c0, v7
	v_add_u32_e32 v14, 0x1cc0, v7
	v_mul_u32_u24_e32 v120, 0x108, v4
	v_add_u32_e32 v120, v120, v6
	v_lshl_add_u32 v15, v120, 2, s30
	v_lshl_add_u32 v122, v3, 13, v2
	v_mov_b32_e32 v123, 0
	v_lshlrev_b32_e32 v124, 4, v4
	v_lshl_add_u32 v124, v6, 11, v124
	v_mov_b32_e32 v125, 0
	s_mov_b64 s[40:41], 0x20000
	s_mov_b64 s[42:43], 0x4000
	s_mov_b64 s[44:45], 0x4000
.Lsg_loop:
	s_lshr_b32 s8, s2, 11
	s_and_b32 s9, s2, 0x7ff
	s_lshr_b32 s10, s9, 7
	s_and_b32 s9, s9, 0x7f
	s_lshl_b32 s24, s10, 19
	s_lshr_b32 s25, s9, 3
	s_lshl_b32 s25, s25, 9
	s_add_i32 s24, s24, s25
	s_and_b32 s25, s9, 3
	s_lshl_b32 s25, s25, 7
	s_add_i32 s24, s24, s25
	s_lshr_b32 s29, s8, 9
	s_lshl_b32 s28, s8, 23
	s_add_u32 s28, s28, s24
	s_addc_u32 s29, s29, 0
	s_bitcmp0_b32 s9, 2
	s_cselect_b32 s24, s4, s34
	s_cselect_b32 s25, s5, s35
	s_add_u32 s28, s28, s24
	s_addc_u32 s29, s29, s25
	s_lshl_b32 s24, s9, 16
	s_lshl_b32 s25, s10, 7
	s_add_i32 s24, s24, s25
	s_lshr_b32 s11, s8, 9
	s_lshl_b32 s10, s8, 23
	s_add_u32 s10, s10, s24
	s_addc_u32 s11, s11, 0
	s_add_u32 s10, s10, s6
	s_addc_u32 s11, s11, s7
	v_lshl_add_u64 v[16:17], s[28:29], 0, v[122:123]
	v_lshl_add_u64 v[18:19], v[16:17], 0, s[44:45]
	v_lshl_add_u64 v[20:21], v[18:19], 0, s[44:45]
	v_lshl_add_u64 v[22:23], v[20:21], 0, s[44:45]
	v_lshl_add_u64 v[24:25], v[22:23], 0, s[44:45]
	v_lshl_add_u64 v[26:27], v[24:25], 0, s[44:45]
	v_lshl_add_u64 v[28:29], v[26:27], 0, s[44:45]
	v_lshl_add_u64 v[30:31], v[28:29], 0, s[44:45]
	global_load_dword v32, v[16:17], off nt
	global_load_dword v33, v[18:19], off nt
	global_load_dword v34, v[20:21], off nt
	global_load_dword v35, v[22:23], off nt
	global_load_dword v36, v[24:25], off nt
	global_load_dword v37, v[26:27], off nt
	global_load_dword v38, v[28:29], off nt
	global_load_dword v39, v[30:31], off nt
	v_lshl_add_u64 v[16:17], v[16:17], 0, s[40:41]
	v_lshl_add_u64 v[18:19], v[18:19], 0, s[40:41]
	v_lshl_add_u64 v[20:21], v[20:21], 0, s[40:41]
	v_lshl_add_u64 v[22:23], v[22:23], 0, s[40:41]
	v_lshl_add_u64 v[24:25], v[24:25], 0, s[40:41]
	v_lshl_add_u64 v[26:27], v[26:27], 0, s[40:41]
	v_lshl_add_u64 v[28:29], v[28:29], 0, s[40:41]
	v_lshl_add_u64 v[30:31], v[30:31], 0, s[40:41]
	global_load_dword v40, v[16:17], off nt
	global_load_dword v41, v[18:19], off nt
	global_load_dword v42, v[20:21], off nt
	global_load_dword v43, v[22:23], off nt
	global_load_dword v44, v[24:25], off nt
	global_load_dword v45, v[26:27], off nt
	global_load_dword v46, v[28:29], off nt
	global_load_dword v47, v[30:31], off nt
	v_lshl_add_u64 v[16:17], v[16:17], 0, s[40:41]
	v_lshl_add_u64 v[18:19], v[18:19], 0, s[40:41]
	v_lshl_add_u64 v[20:21], v[20:21], 0, s[40:41]
	v_lshl_add_u64 v[22:23], v[22:23], 0, s[40:41]
	v_lshl_add_u64 v[24:25], v[24:25], 0, s[40:41]
	v_lshl_add_u64 v[26:27], v[26:27], 0, s[40:41]
	v_lshl_add_u64 v[28:29], v[28:29], 0, s[40:41]
	v_lshl_add_u64 v[30:31], v[30:31], 0, s[40:41]
	global_load_dword v48, v[16:17], off nt
	global_load_dword v49, v[18:19], off nt
	global_load_dword v50, v[20:21], off nt
	global_load_dword v51, v[22:23], off nt
	global_load_dword v52, v[24:25], off nt
	global_load_dword v53, v[26:27], off nt
	global_load_dword v54, v[28:29], off nt
	global_load_dword v55, v[30:31], off nt
	v_lshl_add_u64 v[16:17], v[16:17], 0, s[40:41]
	v_lshl_add_u64 v[18:19], v[18:19], 0, s[40:41]
	v_lshl_add_u64 v[20:21], v[20:21], 0, s[40:41]
	v_lshl_add_u64 v[22:23], v[22:23], 0, s[40:41]
	v_lshl_add_u64 v[24:25], v[24:25], 0, s[40:41]
	v_lshl_add_u64 v[26:27], v[26:27], 0, s[40:41]
	v_lshl_add_u64 v[28:29], v[28:29], 0, s[40:41]
	v_lshl_add_u64 v[30:31], v[30:31], 0, s[40:41]
	global_load_dword v56, v[16:17], off nt
	global_load_dword v57, v[18:19], off nt
	global_load_dword v58, v[20:21], off nt
	global_load_dword v59, v[22:23], off nt
	global_load_dword v60, v[24:25], off nt
	global_load_dword v61, v[26:27], off nt
	global_load_dword v62, v[28:29], off nt
	global_load_dword v63, v[30:31], off nt
	v_lshl_add_u64 v[64:65], s[10:11], 0, v[124:125]
	v_lshl_add_u64 v[66:67], v[64:65], 0, s[42:43]
	v_lshl_add_u64 v[68:69], v[66:67], 0, s[42:43]
	v_lshl_add_u64 v[70:71], v[68:69], 0, s[42:43]
	s_add_i32 s31, s2, 0x300
	s_lshr_b32 s8, s31, 11
	s_and_b32 s9, s31, 0x7ff
	s_lshr_b32 s10, s9, 7
	s_and_b32 s9, s9, 0x7f
	s_lshl_b32 s24, s10, 19
	s_lshr_b32 s25, s9, 3
	s_lshl_b32 s25, s25, 9
	s_add_i32 s24, s24, s25
	s_and_b32 s25, s9, 3
	s_lshl_b32 s25, s25, 7
	s_add_i32 s24, s24, s25
	s_lshr_b32 s29, s8, 9
	s_lshl_b32 s28, s8, 23
	s_add_u32 s28, s28, s24
	s_addc_u32 s29, s29, 0
	s_bitcmp0_b32 s9, 2
	s_cselect_b32 s24, s4, s34
	s_cselect_b32 s25, s5, s35
	s_add_u32 s28, s28, s24
	s_addc_u32 s29, s29, s25
; #define WAVE_LDS_SYNC() do { int _z = 0; (void)emu::wave_xchg(&_z, 4); } while (0)
; #define LAS __attribute__((address_space(3)))
; #define WAVE_LDS_SYNC() asm volatile("s_waitcnt lgkmcnt(0)" ::: "memory")
; #define NT_LOAD(p) __builtin_nontemporal_load(p)
; DEV void tr_item(const float* W, int ldw, int col0, int k0, bf16_t* WT, int K, int row0, LAS float* scr, int lane) {
; #pragma unroll 8
;     for (int i = 0; i < 32; ++i) { const int kk = 2 * i + (lane >> 5); scr[kk * 33 + (lane & 31)] = NT_LOAD(&W[(size_t)(k0 + kk) * ldw + col0 + (lane & 31)]); }
;     WAVE_LDS_SYNC();
	s_lshl_b32 s24, s9, 16
	s_lshl_b32 s25, s10, 7
	s_add_i32 s24, s24, s25
	s_lshr_b32 s11, s8, 9
	s_lshl_b32 s10, s8, 23
	s_add_u32 s10, s10, s24
	s_addc_u32 s11, s11, 0
	s_add_u32 s10, s10, s6
	s_addc_u32 s11, s11, s7
	v_lshl_add_u64 v[16:17], s[28:29], 0, v[122:123]
	v_lshl_add_u64 v[18:19], v[16:17], 0, s[44:45]
	v_lshl_add_u64 v[20:21], v[18:19], 0, s[44:45]
	v_lshl_add_u64 v[22:23], v[20:21], 0, s[44:45]
	v_lshl_add_u64 v[24:25], v[22:23], 0, s[44:45]
	v_lshl_add_u64 v[26:27], v[24:25], 0, s[44:45]
	v_lshl_add_u64 v[28:29], v[26:27], 0, s[44:45]
	v_lshl_add_u64 v[30:31], v[28:29], 0, s[44:45]
	global_load_dword v162, v[16:17], off nt
	global_load_dword v163, v[18:19], off nt
	global_load_dword v164, v[20:21], off nt
	global_load_dword v165, v[22:23], off nt
	global_load_dword v166, v[24:25], off nt
	global_load_dword v167, v[26:27], off nt
	global_load_dword v168, v[28:29], off nt
	global_load_dword v169, v[30:31], off nt
	v_lshl_add_u64 v[16:17], v[16:17], 0, s[40:41]
	v_lshl_add_u64 v[18:19], v[18:19], 0, s[40:41]
	v_lshl_add_u64 v[20:21], v[20:21], 0, s[40:41]
	v_lshl_add_u64 v[22:23], v[22:23], 0, s[40:41]
	v_lshl_add_u64 v[24:25], v[24:25], 0, s[40:41]
	v_lshl_add_u64 v[26:27], v[26:27], 0, s[40:41]
	v_lshl_add_u64 v[28:29], v[28:29], 0, s[40:41]
	v_lshl_add_u64 v[30:31], v[30:31], 0, s[40:41]
	global_load_dword v170, v[16:17], off nt
	global_load_dword v171, v[18:19], off nt
	global_load_dword v172, v[20:21], off nt
	global_load_dword v173, v[22:23], off nt
	global_load_dword v174, v[24:25], off nt
	global_load_dword v175, v[26:27], off nt
	global_load_dword v176, v[28:29], off nt
	global_load_dword v177, v[30:31], off nt
	v_lshl_add_u64 v[16:17], v[16:17], 0, s[40:41]
	v_lshl_add_u64 v[18:19], v[18:19], 0, s[40:41]
	v_lshl_add_u64 v[20:21], v[20:21], 0, s[40:41]
	v_lshl_add_u64 v[22:23], v[22:23], 0, s[40:41]
	v_lshl_add_u64 v[24:25], v[24:25], 0, s[40:41]
	v_lshl_add_u64 v[26:27], v[26:27], 0, s[40:41]
	v_lshl_add_u64 v[28:29], v[28:29], 0, s[40:41]
	v_lshl_add_u64 v[30:31], v[30:31], 0, s[40:41]
	global_load_dword v178, v[16:17], off nt
	global_load_dword v179, v[18:19], off nt
	global_load_dword v180, v[20:21], off nt
	global_load_dword v181, v[22:23], off nt
	global_load_dword v182, v[24:25], off nt
	global_load_dword v183, v[26:27], off nt
	global_load_dword v184, v[28:29], off nt
	global_load_dword v185, v[30:31], off nt
	v_lshl_add_u64 v[16:17], v[16:17], 0, s[40:41]
	v_lshl_add_u64 v[18:19], v[18:19], 0, s[40:41]
	v_lshl_add_u64 v[20:21], v[20:21], 0, s[40:41]
	v_lshl_add_u64 v[22:23], v[22:23], 0, s[40:41]
	v_lshl_add_u64 v[24:25], v[24:25], 0, s[40:41]
	v_lshl_add_u64 v[26:27], v[26:27], 0, s[40:41]
	v_lshl_add_u64 v[28:29], v[28:29], 0, s[40:41]
	v_lshl_add_u64 v[30:31], v[30:31], 0, s[40:41]
	global_load_dword v186, v[16:17], off nt
	global_load_dword v187, v[18:19], off nt
	global_load_dword v188, v[20:21], off nt
	global_load_dword v189, v[22:23], off nt
	global_load_dword v190, v[24:25], off nt
	global_load_dword v191, v[26:27], off nt
	global_load_dword v192, v[28:29], off nt
	global_load_dword v193, v[30:31], off nt
	v_lshl_add_u64 v[126:127], s[10:11], 0, v[124:125]
	v_lshl_add_u64 v[128:129], v[126:127], 0, s[42:43]
	v_lshl_add_u64 v[130:131], v[128:129], 0, s[42:43]
	v_lshl_add_u64 v[132:133], v[130:131], 0, s[42:43]
	s_waitcnt vmcnt(62)
	ds_write2_b32 v7, v32, v33 offset1:66
	s_waitcnt vmcnt(60)
	ds_write2_b32 v7, v34, v35 offset0:132 offset1:198
	s_waitcnt vmcnt(58)
	ds_write2_b32 v8, v36, v37 offset0:8 offset1:74
	s_waitcnt vmcnt(56)
	ds_write2_b32 v8, v38, v39 offset0:140 offset1:206
	s_waitcnt vmcnt(54)
	ds_write2_b32 v9, v40, v41 offset1:66
	s_waitcnt vmcnt(52)
	ds_write2_b32 v9, v42, v43 offset0:132 offset1:198
	s_waitcnt vmcnt(50)
	ds_write2_b32 v10, v44, v45 offset0:8 offset1:74
	s_waitcnt vmcnt(48)
	ds_write2_b32 v10, v46, v47 offset0:140 offset1:206
	s_waitcnt vmcnt(46)
	ds_write2_b32 v11, v48, v49 offset1:66
	s_waitcnt vmcnt(44)
	ds_write2_b32 v11, v50, v51 offset0:132 offset1:198
	s_waitcnt vmcnt(42)
	ds_write2_b32 v12, v52, v53 offset0:8 offset1:74
	s_waitcnt vmcnt(40)
	ds_write2_b32 v12, v54, v55 offset0:140 offset1:206
	s_waitcnt vmcnt(38)
	ds_write2_b32 v13, v56, v57 offset1:66
	s_waitcnt vmcnt(36)
	ds_write2_b32 v13, v58, v59 offset0:132 offset1:198
	s_waitcnt vmcnt(34)
	ds_write2_b32 v14, v60, v61 offset0:8 offset1:74
	s_waitcnt vmcnt(32)
; #define WAVE_LDS_SYNC() do { int _z = 0; (void)emu::wave_xchg(&_z, 4); } while (0)
; #define LAS __attribute__((address_space(3)))
; #define WAVE_LDS_SYNC() asm volatile("s_waitcnt lgkmcnt(0)" ::: "memory")
; #define NT_STORE(v, p) __builtin_nontemporal_store((v), (p))
; DEV unsigned pk2(float lo, float hi) { return f2bf(lo) | (f2bf(hi) << 16); }
; DEV unsigned pk2(float lo, float hi) { const f32x2n_t v = {lo, hi}; return __builtin_bit_cast(unsigned, __builtin_convertvector(v, bf16x2n_t)); }
; DEV void tr_item(const float* W, int ldw, int col0, int k0, bf16_t* WT, int K, int row0, LAS float* scr, int lane) {
;     ...
;     WAVE_LDS_SYNC();
;     const int c = lane & 7;
; #pragma unroll
;     for (int j = 0; j < 4; ++j) { const int n = (lane >> 3) + 8 * j; const LAS float* s = scr + (8 * c) * 33 + n;
;         u32x4 o; o.x = pk2(s[0 * 33], s[1 * 33]); o.y = pk2(s[2 * 33], s[3 * 33]); o.z = pk2(s[4 * 33], s[5 * 33]); o.w = pk2(s[6 * 33], s[7 * 33]);
;         NT_STORE(o, (u32x4*)(WT + (size_t)(row0 + n) * K + k0 + 8 * c)); }
	ds_write2_b32 v14, v62, v63 offset0:140 offset1:206
	ds_read2_b32 v[72:73], v15 offset1:8
	ds_read2_b32 v[74:75], v15 offset0:33 offset1:41
	ds_read2_b32 v[76:77], v15 offset0:66 offset1:74
	ds_read2_b32 v[78:79], v15 offset0:99 offset1:107
	ds_read2_b32 v[80:81], v15 offset0:132 offset1:140
	ds_read2_b32 v[82:83], v15 offset0:165 offset1:173
	ds_read2_b32 v[84:85], v15 offset0:198 offset1:206
	ds_read2_b32 v[86:87], v15 offset0:231 offset1:239
	ds_read2_b32 v[88:89], v15 offset0:16 offset1:24
	ds_read2_b32 v[90:91], v15 offset0:49 offset1:57
	ds_read2_b32 v[92:93], v15 offset0:82 offset1:90
	ds_read2_b32 v[94:95], v15 offset0:115 offset1:123
	s_waitcnt lgkmcnt(4)
	v_cvt_pk_bf16_f32 v104, v72, v74
	v_cvt_pk_bf16_f32 v105, v76, v78
	v_cvt_pk_bf16_f32 v106, v80, v82
	v_cvt_pk_bf16_f32 v107, v84, v86
	v_cvt_pk_bf16_f32 v108, v73, v75
	v_cvt_pk_bf16_f32 v109, v77, v79
	v_cvt_pk_bf16_f32 v110, v81, v83
	v_cvt_pk_bf16_f32 v111, v85, v87
	ds_read2_b32 v[96:97], v15 offset0:148 offset1:156
	ds_read2_b32 v[98:99], v15 offset0:181 offset1:189
	ds_read2_b32 v[100:101], v15 offset0:214 offset1:222
	ds_read2_b32 v[102:103], v15 offset0:247 offset1:255
	global_store_dwordx4 v[64:65], v[104:107], off nt
	global_store_dwordx4 v[66:67], v[108:111], off nt
	s_waitcnt lgkmcnt(0)
	v_cvt_pk_bf16_f32 v112, v88, v90
	v_cvt_pk_bf16_f32 v113, v92, v94
	v_cvt_pk_bf16_f32 v114, v96, v98
	v_cvt_pk_bf16_f32 v115, v100, v102
	v_cvt_pk_bf16_f32 v116, v89, v91
	v_cvt_pk_bf16_f32 v117, v93, v95
	v_cvt_pk_bf16_f32 v118, v97, v99
	v_cvt_pk_bf16_f32 v119, v101, v103
	global_store_dwordx4 v[68:69], v[112:115], off nt
	global_store_dwordx4 v[70:71], v[116:119], off nt
	s_waitcnt vmcnt(34)
	ds_write2_b32 v7, v162, v163 offset1:66
	s_waitcnt vmcnt(32)
	ds_write2_b32 v7, v164, v165 offset0:132 offset1:198
	s_waitcnt vmcnt(30)
	ds_write2_b32 v8, v166, v167 offset0:8 offset1:74
	s_waitcnt vmcnt(28)
	ds_write2_b32 v8, v168, v169 offset0:140 offset1:206
	s_waitcnt vmcnt(26)
	ds_write2_b32 v9, v170, v171 offset1:66
	s_waitcnt vmcnt(24)
	ds_write2_b32 v9, v172, v173 offset0:132 offset1:198
	s_waitcnt vmcnt(22)
	ds_write2_b32 v10, v174, v175 offset0:8 offset1:74
	s_waitcnt vmcnt(20)
	ds_write2_b32 v10, v176, v177 offset0:140 offset1:206
	s_waitcnt vmcnt(18)
	ds_write2_b32 v11, v178, v179 offset1:66
	s_waitcnt vmcnt(16)
	ds_write2_b32 v11, v180, v181 offset0:132 offset1:198
	s_waitcnt vmcnt(14)
	ds_write2_b32 v12, v182, v183 offset0:8 offset1:74
	s_waitcnt vmcnt(12)
	ds_write2_b32 v12, v184, v185 offset0:140 offset1:206
	s_waitcnt vmcnt(10)
	ds_write2_b32 v13, v186, v187 offset1:66
	s_waitcnt vmcnt(8)
	ds_write2_b32 v13, v188, v189 offset0:132 offset1:198
	s_waitcnt vmcnt(6)
	ds_write2_b32 v14, v190, v191 offset0:8 offset1:74
	s_waitcnt vmcnt(4)
	ds_write2_b32 v14, v192, v193 offset0:140 offset1:206
	ds_read2_b32 v[72:73], v15 offset1:8
	ds_read2_b32 v[74:75], v15 offset0:33 offset1:41
	ds_read2_b32 v[76:77], v15 offset0:66 offset1:74
	ds_read2_b32 v[78:79], v15 offset0:99 offset1:107
	ds_read2_b32 v[80:81], v15 offset0:132 offset1:140
	ds_read2_b32 v[82:83], v15 offset0:165 offset1:173
	ds_read2_b32 v[84:85], v15 offset0:198 offset1:206
	ds_read2_b32 v[86:87], v15 offset0:231 offset1:239
	ds_read2_b32 v[88:89], v15 offset0:16 offset1:24
	ds_read2_b32 v[90:91], v15 offset0:49 offset1:57
	ds_read2_b32 v[92:93], v15 offset0:82 offset1:90
	ds_read2_b32 v[94:95], v15 offset0:115 offset1:123
	s_waitcnt lgkmcnt(4)
	v_cvt_pk_bf16_f32 v104, v72, v74
	v_cvt_pk_bf16_f32 v105, v76, v78
	v_cvt_pk_bf16_f32 v106, v80, v82
	v_cvt_pk_bf16_f32 v107, v84, v86
	v_cvt_pk_bf16_f32 v108, v73, v75
	v_cvt_pk_bf16_f32 v109, v77, v79
	v_cvt_pk_bf16_f32 v110, v81, v83
	v_cvt_pk_bf16_f32 v111, v85, v87
	ds_read2_b32 v[96:97], v15 offset0:148 offset1:156
	ds_read2_b32 v[98:99], v15 offset0:181 offset1:189
	ds_read2_b32 v[100:101], v15 offset0:214 offset1:222
	ds_read2_b32 v[102:103], v15 offset0:247 offset1:255
	global_store_dwordx4 v[126:127], v[104:107], off nt
	global_store_dwordx4 v[128:129], v[108:111], off nt
	s_waitcnt lgkmcnt(0)
	v_cvt_pk_bf16_f32 v112, v88, v90
	v_cvt_pk_bf16_f32 v113, v92, v94
	v_cvt_pk_bf16_f32 v114, v96, v98
	v_cvt_pk_bf16_f32 v115, v100, v102
	v_cvt_pk_bf16_f32 v116, v89, v91
	v_cvt_pk_bf16_f32 v117, v93, v95
	v_cvt_pk_bf16_f32 v118, v97, v99
	v_cvt_pk_bf16_f32 v119, v101, v103
	global_store_dwordx4 v[130:131], v[112:115], off nt
	global_store_dwordx4 v[132:133], v[116:119], off nt
	s_add_i32 s2, s2, 0x600
	s_cmp_lt_u32 s2, 0x3000
	s_cbranch_scc1 .Lsg_loop
